# P1->P2 pair barrier made two-level: XCD-local arrival counter, only the last workgroup of each XCD does the L2 write-back (one buffer_wbl2 per XCD instead of 32)
# speedup vs baseline: 1.0164x; 1.0059x over previous
; __device__ __forceinline__ unsigned xb_ld(unsigned* p)              { return __hip_atomic_load(p, __ATOMIC_RELAXED, __HIP_MEMORY_SCOPE_AGENT); }
; __device__ __forceinline__ unsigned xb_add(unsigned* p, unsigned v) { return __hip_atomic_fetch_add(p, v, __ATOMIC_RELAXED, __HIP_MEMORY_SCOPE_AGENT); }
; #define XB_SPIN(cond, bar) do { unsigned _sp = 0; while (cond) { __builtin_amdgcn_s_sleep(1); \
;     if ((++_sp & 255u) == 0u) { if (xb_ld(&(bar)[XB_TMO])) break; if (_sp > XB_SPIN_CAP) { atomicAdd(&(bar)[XB_TMO], 1u); break; } } } } while (0)
; __device__ __forceinline__ void xcd_barrier(const XcdBarrier& b) {
;     asm volatile("s_waitcnt vmcnt(0)" ::: "memory");
;     __syncthreads();
;     if (threadIdx.x == 0) {
;         unsigned* bar = b.bar;
;         __builtin_amdgcn_s_waitcnt(0);
;         unsigned nloc = b.st[0], nx = b.st[1];
;         if (nloc == 0u) { xcd_barrier_complete(bar, b.x, nloc, nx); b.st[0] = nloc; b.st[1] = nx; }
;         const unsigned old = xb_add(&bar[XB_XSUB(b.x)], 1u);
;         const unsigned gen = old / nloc;
;         if (old + 1u == (gen + 1u) * nloc) {
;             __builtin_amdgcn_fence(__ATOMIC_RELEASE, "agent");
;             asm volatile("s_waitcnt vmcnt(0)" ::: "memory");
;             const unsigned og = xb_add(&bar[XB_TOP], 1u);
;             const unsigned tg = og / nx;
;             if (og + 1u == (tg + 1u) * nx) xb_add(&bar[XB_TOPGEN], 1u);
;             else XB_SPIN(xb_ld(&bar[XB_TOPGEN]) == tg, bar);
;             __builtin_amdgcn_fence(__ATOMIC_ACQUIRE, "agent");
;             xb_add(&bar[XB_XGEN(b.x)], 1u);
;             asm volatile("s_waitcnt vmcnt(0)" ::: "memory");
;         } else {
;             XB_SPIN(xb_ld(&bar[XB_XGEN(b.x)]) == gen, bar);
;             __builtin_amdgcn_fence(__ATOMIC_ACQUIRE, "agent");
;             asm volatile("s_waitcnt vmcnt(0)" ::: "memory");
;         }
;     }
;     __syncthreads();
; }
.LBB0_192:
	s_waitcnt vmcnt(0)
	s_waitcnt vmcnt(0) lgkmcnt(0)
	s_barrier
	s_mov_b64 s[2:3], exec
	v_readlane_b32 s12, v253, 36
	v_readlane_b32 s13, v253, 37
	s_and_b64 s[12:13], s[2:3], s[12:13]
	s_mov_b64 exec, s[12:13]
	s_cbranch_execz .LBB0_244
	s_cmp_lg_u32 s98, 0
	s_cbranch_scc0 .Lgb_full_244
	v_readlane_b32 s4, v253, 1
	v_readlane_b32 s12, v253, 56
	v_readlane_b32 s13, v253, 57
	s_nop 3
	s_and_b32 s17, s4, 7
	s_lshl_b32 s17, s17, 6
	s_add_i32 s17, s17, 0x7400
	v_mov_b32_e32 v4, s17
	s_bfe_u32 s4, s4, 0x20001
	s_lshl_b32 s4, s4, 8
	s_add_i32 s4, s4, 0x7000
	v_mov_b32_e32 v2, s4
	s_add_i32 s16, s92, 1
	s_lshl_b32 s17, s16, 5
	s_lshl_b32 s16, s16, 1
	s_mov_b32 s1, 0
	s_nop 1
	global_atomic_add v5, v4, v234, s[12:13] sc0
	s_waitcnt vmcnt(0)
	v_readfirstlane_b32 s4, v5
	s_nop 3
	s_add_i32 s4, s4, 1
	s_cmp_lg_u32 s4, s17
	s_cbranch_scc1 .Lgb_pair_244
	buffer_wbl2 sc1
	s_waitcnt vmcnt(0)
	global_atomic_add v2, v234, s[12:13]
	s_waitcnt vmcnt(0)
